# scan pass 2 rebalanced 14/14 (the 14 heaviest attention q-tile pairs hand their scan chunk to the 14 lightest)
# baseline (speedup 1.0000x reference)
; DEV int ltid() { int t = threadIdx.x; asm volatile("" : "+v"(t)); return t; }
; DEV void ph_scan2(const Params& p, int item) {
;   const int b = item / NCH, c = item % NCH, ch = ltid() * 4;
;   float H[4] = {0.f, 0.f, 0.f, 0.f};
;   for (int c2 = 0; c2 < c; ++c2) {
;     float4 a = *(const float4*)(p.csA + (size_t)(b * NCH + c2) * 1024 + ch);
;     float4 hh = *(const float4*)(p.csH + (size_t)(b * NCH + c2) * 1024 + ch);
;     H[0] = a.x * H[0] + hh.x; H[1] = a.y * H[1] + hh.y; H[2] = a.z * H[2] + hh.z; H[3] = a.w * H[3] + hh.w;
;   }
;   const size_t row0 = (size_t)(b * S_ + c * CHL);
.Lp6_entry:
	v_mov_b32_e32 v1, v0
	s_cmpk_gt_i32 s94, 0x1ff
	s_waitcnt lgkmcnt(0)
	s_barrier
	s_cbranch_scc1 .LBB0_1132
	s_mov_b64 exec, -1
	v_lshlrev_b32_e32 v1, 4, v0
	v_lshlrev_b32_e32 v2, 3, v0
	v_mov_b32_e32 v8, 0x3ba10414
	v_mov_b32_e32 v9, 0xb9c68948
	v_mov_b32_e32 v3, 0x7f800000
	s_mov_b32 s72, 0x378e98ab
	s_mov_b32 s73, 0x3b7cd369
	s_mov_b32 s74, 0xbcc618b2
	s_mov_b32 s75, 0x3dda74e4
	s_mov_b32 s76, 0x3f228afd
	s_mov_b32 s77, 0x3e03c728
	s_mov_b32 s78, 0xbfb8aa3b
	s_mov_b32 s79, 0x42ce8ed0
	s_mov_b32 s80, 0xc2b17218
	s_brev_b32 s81, -2
	s_mov_b32 s50, s94
	s_lshr_b32 s8, s94, 4
	s_cmp_gt_u32 s8, 17
	s_cbranch_scc1 .Lsc_end

; DEV unsigned pack2(float a, float b) { float2v v = {a, b}; return __builtin_bit_cast(unsigned, __builtin_convertvector(v, bf16x2v)); }
; DEV float bflo(unsigned u) { return __uint_as_float(u << 16); }
; DEV float bfhi(unsigned u) { return __uint_as_float(u & 0xffff0000u); }
; DEV float gelu_exact(float v) { return 0.5f * v * (1.f + erff(v * 0.7071067811865476f)); }
; DEV void ph_scan2(const Params& p, int item) {
;     ...
;   for (int t = 0; t < CHL; ++t) {
;     float4 a = *(const float4*)(p.a_arr + (row0 + t) * 1024 + ch);
;     float4 bb = *(const float4*)(p.b_arr + (row0 + t) * 1024 + ch);
;     u32x2 xg = *(const u32x2*)(p.z + (row0 + t) * ZLD + CXG + ch);
;     H[0] = a.x * H[0] + bb.x; H[1] = a.y * H[1] + bb.y; H[2] = a.z * H[2] + bb.z; H[3] = a.w * H[3] + bb.w;
;     u32x2 pk;
;     pk[0] = pack2(gelu_exact(bflo(xg[0])) * H[0], gelu_exact(bfhi(xg[0])) * H[1]);
;     pk[1] = pack2(gelu_exact(bflo(xg[1])) * H[2], gelu_exact(bfhi(xg[1])) * H[3]);
;     *(u32x2*)(p.orn + (row0 + t) * 1024 + ch) = pk;
;   }
.Lsc_main:
	global_load_dwordx4 v[80:83], v1, s[2:3] sc0 sc1 nt
	global_load_dwordx4 v[84:87], v1, s[4:5] sc0 sc1 nt
	global_load_dwordx2 v[88:89], v2, s[6:7] sc0 sc1 nt
	s_add_u32 s2, s2, 0x1000
	s_addc_u32 s3, s3, 0
	s_add_u32 s4, s4, 0x1000
	s_addc_u32 s5, s5, 0
	s_add_u32 s6, s6, 0x2500
	s_addc_u32 s7, s7, 0
	global_load_dwordx4 v[90:93], v1, s[2:3] sc0 sc1 nt
	global_load_dwordx4 v[94:97], v1, s[4:5] sc0 sc1 nt
	global_load_dwordx2 v[98:99], v2, s[6:7] sc0 sc1 nt
	s_add_u32 s2, s2, 0x1000
	s_addc_u32 s3, s3, 0
	s_add_u32 s4, s4, 0x1000
	s_addc_u32 s5, s5, 0
	s_add_u32 s6, s6, 0x2500
	s_addc_u32 s7, s7, 0
	global_load_dwordx4 v[100:103], v1, s[2:3] sc0 sc1 nt
	global_load_dwordx4 v[104:107], v1, s[4:5] sc0 sc1 nt
	global_load_dwordx2 v[108:109], v2, s[6:7] sc0 sc1 nt
	s_add_u32 s2, s2, 0x1000
	s_addc_u32 s3, s3, 0
	s_add_u32 s4, s4, 0x1000
	s_addc_u32 s5, s5, 0
	s_add_u32 s6, s6, 0x2500
	s_addc_u32 s7, s7, 0
	global_load_dwordx4 v[110:113], v1, s[2:3] sc0 sc1 nt
	global_load_dwordx4 v[114:117], v1, s[4:5] sc0 sc1 nt
	global_load_dwordx2 v[118:119], v2, s[6:7] sc0 sc1 nt
	s_add_u32 s2, s2, 0x1000
	s_addc_u32 s3, s3, 0
	s_add_u32 s4, s4, 0x1000
	s_addc_u32 s5, s5, 0
	s_add_u32 s6, s6, 0x2500
	s_addc_u32 s7, s7, 0
	global_load_dwordx4 v[120:123], v1, s[2:3] sc0 sc1 nt
	global_load_dwordx4 v[124:127], v1, s[4:5] sc0 sc1 nt
	global_load_dwordx2 v[128:129], v2, s[6:7] sc0 sc1 nt
	s_add_u32 s2, s2, 0x1000
	s_addc_u32 s3, s3, 0
	s_add_u32 s4, s4, 0x1000
	s_addc_u32 s5, s5, 0
	s_add_u32 s6, s6, 0x2500
	s_addc_u32 s7, s7, 0
	global_load_dwordx4 v[130:133], v1, s[2:3] sc0 sc1 nt
	global_load_dwordx4 v[134:137], v1, s[4:5] sc0 sc1 nt
	global_load_dwordx2 v[138:139], v2, s[6:7] sc0 sc1 nt
	s_add_u32 s2, s2, 0x1000
	s_addc_u32 s3, s3, 0
	s_add_u32 s4, s4, 0x1000
	s_addc_u32 s5, s5, 0
	s_add_u32 s6, s6, 0x2500
	s_addc_u32 s7, s7, 0
	global_load_dwordx4 v[140:143], v1, s[2:3] sc0 sc1 nt
	global_load_dwordx4 v[144:147], v1, s[4:5] sc0 sc1 nt
	global_load_dwordx2 v[148:149], v2, s[6:7] sc0 sc1 nt
	s_add_u32 s2, s2, 0x1000
	s_addc_u32 s3, s3, 0
	s_add_u32 s4, s4, 0x1000
	s_addc_u32 s5, s5, 0
	s_add_u32 s6, s6, 0x2500
	s_addc_u32 s7, s7, 0
	global_load_dwordx4 v[150:153], v1, s[2:3] sc0 sc1 nt
	global_load_dwordx4 v[154:157], v1, s[4:5] sc0 sc1 nt
	global_load_dwordx2 v[158:159], v2, s[6:7] sc0 sc1 nt
	s_add_u32 s2, s2, 0x1000
	s_addc_u32 s3, s3, 0
	s_add_u32 s4, s4, 0x1000
	s_addc_u32 s5, s5, 0
	s_add_u32 s6, s6, 0x2500
	s_addc_u32 s7, s7, 0
	s_waitcnt vmcnt(21)
	v_fma_f32 v4, v80, v4, v84
	v_fma_f32 v5, v81, v5, v85
	v_fma_f32 v6, v82, v6, v86
	v_fma_f32 v7, v83, v7, v87
	v_lshlrev_b32_e32 v168, 16, v88
	v_and_b32_e32 v169, 0xffff0000, v88
	v_lshlrev_b32_e32 v170, 16, v89
	v_and_b32_e32 v171, 0xffff0000, v89
	v_mul_f32_e32 v160, 0x3f3504f3, v168
	v_mul_f32_e32 v161, v160, v160
	v_fmamk_f32 v162, v161, 0xba1345e1, v8
	v_fmaak_f32 v162, v161, v162, 0xbcdac9b8
	v_fmaak_f32 v162, v161, v162, 0x3de703be
	v_fmaak_f32 v162, v161, v162, 0xbec09330
	v_fmaak_f32 v161, v161, v162, 0x3e0375d0
	v_fma_f32 v165, |v160|, v161, |v160|
	v_fma_f32 v161, |v160|, s72, v9
	v_fma_f32 v161, |v160|, v161, s73
	v_fma_f32 v161, |v160|, v161, s74
	v_fma_f32 v161, |v160|, v161, s75
	v_fma_f32 v161, |v160|, v161, s76
	v_fma_f32 v161, |v160|, v161, s77
	v_fma_f32 v161, |v160|, v161, |v160|
	v_mul_f32_e32 v162, 0xbfb8aa3b, v161
	v_fma_f32 v163, v161, s78, -v162
	v_rndne_f32_e32 v164, v162
	v_fmac_f32_e32 v163, 0xb2a5705f, v161
	v_sub_f32_e32 v162, v162, v164
	v_add_f32_e32 v162, v162, v163
	v_cvt_i32_f32_e32 v163, v164
	v_exp_f32_e32 v162, v162
	v_cmp_nlt_f32_e32 vcc, s79, v161
	v_ldexp_f32 v162, v162, v163
	s_nop 0
	v_cndmask_b32_e32 v162, 0, v162, vcc
	v_cmp_ngt_f32_e32 vcc, s80, v161
	s_nop 1
	v_cndmask_b32_e32 v161, v3, v162, vcc
	v_sub_f32_e32 v166, 1.0, v161
	v_cmp_lt_f32_e64 vcc, |v160|, 1.0
	s_nop 1
	v_cndmask_b32_e32 v165, v166, v165, vcc
	v_bfi_b32 v165, s81, v165, v160
	v_mul_f32_e32 v161, 0.5, v168
	v_add_f32_e32 v165, 1.0, v165
	v_mul_f32_e32 v161, v161, v165
	v_mul_f32_e32 v176, v161, v4
	v_mul_f32_e32 v160, 0x3f3504f3, v169
	v_mul_f32_e32 v161, v160, v160
	v_fmamk_f32 v162, v161, 0xba1345e1, v8
	v_fmaak_f32 v162, v161, v162, 0xbcdac9b8
	v_fmaak_f32 v162, v161, v162, 0x3de703be
	v_fmaak_f32 v162, v161, v162, 0xbec09330
	v_fmaak_f32 v161, v161, v162, 0x3e0375d0
	v_fma_f32 v165, |v160|, v161, |v160|
	v_fma_f32 v161, |v160|, s72, v9
	v_fma_f32 v161, |v160|, v161, s73
	v_fma_f32 v161, |v160|, v161, s74
	v_fma_f32 v161, |v160|, v161, s75
	v_fma_f32 v161, |v160|, v161, s76
	v_fma_f32 v161, |v160|, v161, s77
	v_fma_f32 v161, |v160|, v161, |v160|
	v_mul_f32_e32 v162, 0xbfb8aa3b, v161
	v_fma_f32 v163, v161, s78, -v162
	v_rndne_f32_e32 v164, v162
	v_fmac_f32_e32 v163, 0xb2a5705f, v161
	v_sub_f32_e32 v162, v162, v164
	v_add_f32_e32 v162, v162, v163
	v_cvt_i32_f32_e32 v163, v164
	v_exp_f32_e32 v162, v162
	v_cmp_nlt_f32_e32 vcc, s79, v161
	v_ldexp_f32 v162, v162, v163
	s_nop 0
	v_cndmask_b32_e32 v162, 0, v162, vcc
	v_cmp_ngt_f32_e32 vcc, s80, v161
	s_nop 1
	v_cndmask_b32_e32 v161, v3, v162, vcc
	v_sub_f32_e32 v166, 1.0, v161
	v_cmp_lt_f32_e64 vcc, |v160|, 1.0
	s_nop 1
	v_cndmask_b32_e32 v165, v166, v165, vcc
	v_bfi_b32 v165, s81, v165, v160
	v_mul_f32_e32 v161, 0.5, v169
	v_add_f32_e32 v165, 1.0, v165
	v_mul_f32_e32 v161, v161, v165
	v_mul_f32_e32 v177, v161, v5
	v_mul_f32_e32 v160, 0x3f3504f3, v170
	v_mul_f32_e32 v161, v160, v160
	v_fmamk_f32 v162, v161, 0xba1345e1, v8
	v_fmaak_f32 v162, v161, v162, 0xbcdac9b8
	v_fmaak_f32 v162, v161, v162, 0x3de703be
	v_fmaak_f32 v162, v161, v162, 0xbec09330
	v_fmaak_f32 v161, v161, v162, 0x3e0375d0
	v_fma_f32 v165, |v160|, v161, |v160|
; DEV unsigned pack2(float a, float b) { float2v v = {a, b}; return __builtin_bit_cast(unsigned, __builtin_convertvector(v, bf16x2v)); }
; DEV float bflo(unsigned u) { return __uint_as_float(u << 16); }
; DEV float bfhi(unsigned u) { return __uint_as_float(u & 0xffff0000u); }
; DEV float gelu_exact(float v) { return 0.5f * v * (1.f + erff(v * 0.7071067811865476f)); }
; DEV void ph_scan2(const Params& p, int item) {
;     ...
;   for (int t = 0; t < CHL; ++t) {
;     float4 a = *(const float4*)(p.a_arr + (row0 + t) * 1024 + ch);
;     float4 bb = *(const float4*)(p.b_arr + (row0 + t) * 1024 + ch);
;     u32x2 xg = *(const u32x2*)(p.z + (row0 + t) * ZLD + CXG + ch);
;     H[0] = a.x * H[0] + bb.x; H[1] = a.y * H[1] + bb.y; H[2] = a.z * H[2] + bb.z; H[3] = a.w * H[3] + bb.w;
;     u32x2 pk;
;     pk[0] = pack2(gelu_exact(bflo(xg[0])) * H[0], gelu_exact(bfhi(xg[0])) * H[1]);
;     pk[1] = pack2(gelu_exact(bflo(xg[1])) * H[2], gelu_exact(bfhi(xg[1])) * H[3]);
;     *(u32x2*)(p.orn + (row0 + t) * 1024 + ch) = pk;
;   }
	v_fma_f32 v161, |v160|, s72, v9
	v_fma_f32 v161, |v160|, v161, s73
	v_fma_f32 v161, |v160|, v161, s74
	v_fma_f32 v161, |v160|, v161, s75
	v_fma_f32 v161, |v160|, v161, s76
	v_fma_f32 v161, |v160|, v161, s77
	v_fma_f32 v161, |v160|, v161, |v160|
	v_mul_f32_e32 v162, 0xbfb8aa3b, v161
	v_fma_f32 v163, v161, s78, -v162
	v_rndne_f32_e32 v164, v162
	v_fmac_f32_e32 v163, 0xb2a5705f, v161
	v_sub_f32_e32 v162, v162, v164
	v_add_f32_e32 v162, v162, v163
	v_cvt_i32_f32_e32 v163, v164
	v_exp_f32_e32 v162, v162
	v_cmp_nlt_f32_e32 vcc, s79, v161
	v_ldexp_f32 v162, v162, v163
	s_nop 0
	v_cndmask_b32_e32 v162, 0, v162, vcc
	v_cmp_ngt_f32_e32 vcc, s80, v161
	s_nop 1
	v_cndmask_b32_e32 v161, v3, v162, vcc
	v_sub_f32_e32 v166, 1.0, v161
	v_cmp_lt_f32_e64 vcc, |v160|, 1.0
	s_nop 1
	v_cndmask_b32_e32 v165, v166, v165, vcc
	v_bfi_b32 v165, s81, v165, v160
	v_mul_f32_e32 v161, 0.5, v170
	v_add_f32_e32 v165, 1.0, v165
	v_mul_f32_e32 v161, v161, v165
	v_mul_f32_e32 v178, v161, v6
	v_mul_f32_e32 v160, 0x3f3504f3, v171
	v_mul_f32_e32 v161, v160, v160
	v_fmamk_f32 v162, v161, 0xba1345e1, v8
	v_fmaak_f32 v162, v161, v162, 0xbcdac9b8
	v_fmaak_f32 v162, v161, v162, 0x3de703be
	v_fmaak_f32 v162, v161, v162, 0xbec09330
	v_fmaak_f32 v161, v161, v162, 0x3e0375d0
	v_fma_f32 v165, |v160|, v161, |v160|
	v_fma_f32 v161, |v160|, s72, v9
	v_fma_f32 v161, |v160|, v161, s73
	v_fma_f32 v161, |v160|, v161, s74
	v_fma_f32 v161, |v160|, v161, s75
	v_fma_f32 v161, |v160|, v161, s76
	v_fma_f32 v161, |v160|, v161, s77
	v_fma_f32 v161, |v160|, v161, |v160|
	v_mul_f32_e32 v162, 0xbfb8aa3b, v161
	v_fma_f32 v163, v161, s78, -v162
	v_rndne_f32_e32 v164, v162
	v_fmac_f32_e32 v163, 0xb2a5705f, v161
	v_sub_f32_e32 v162, v162, v164
	v_add_f32_e32 v162, v162, v163
	v_cvt_i32_f32_e32 v163, v164
	v_exp_f32_e32 v162, v162
	v_cmp_nlt_f32_e32 vcc, s79, v161
	v_ldexp_f32 v162, v162, v163
	s_nop 0
	v_cndmask_b32_e32 v162, 0, v162, vcc
	v_cmp_ngt_f32_e32 vcc, s80, v161
	s_nop 1
	v_cndmask_b32_e32 v161, v3, v162, vcc
	v_sub_f32_e32 v166, 1.0, v161
	v_cmp_lt_f32_e64 vcc, |v160|, 1.0
	s_nop 1
	v_cndmask_b32_e32 v165, v166, v165, vcc
	v_bfi_b32 v165, s81, v165, v160
	v_mul_f32_e32 v161, 0.5, v171
	v_add_f32_e32 v165, 1.0, v165
	v_mul_f32_e32 v161, v161, v165
	v_mul_f32_e32 v179, v161, v7
	v_cvt_pk_bf16_f32 v180, v176, v177
	v_cvt_pk_bf16_f32 v181, v178, v179
	global_store_dwordx2 v2, v[180:181], s[34:35]
	s_add_u32 s34, s34, 0x800
	s_addc_u32 s35, s35, 0
	s_waitcnt vmcnt(19)
	v_fma_f32 v4, v90, v4, v94
	v_fma_f32 v5, v91, v5, v95
	v_fma_f32 v6, v92, v6, v96
	v_fma_f32 v7, v93, v7, v97
	v_lshlrev_b32_e32 v168, 16, v98
	v_and_b32_e32 v169, 0xffff0000, v98
	v_lshlrev_b32_e32 v170, 16, v99
	v_and_b32_e32 v171, 0xffff0000, v99
	v_mul_f32_e32 v160, 0x3f3504f3, v168
	v_mul_f32_e32 v161, v160, v160
	v_fmamk_f32 v162, v161, 0xba1345e1, v8
	v_fmaak_f32 v162, v161, v162, 0xbcdac9b8
	v_fmaak_f32 v162, v161, v162, 0x3de703be
	v_fmaak_f32 v162, v161, v162, 0xbec09330
	v_fmaak_f32 v161, v161, v162, 0x3e0375d0
	v_fma_f32 v165, |v160|, v161, |v160|
	v_fma_f32 v161, |v160|, s72, v9
	v_fma_f32 v161, |v160|, v161, s73
	v_fma_f32 v161, |v160|, v161, s74
	v_fma_f32 v161, |v160|, v161, s75
	v_fma_f32 v161, |v160|, v161, s76
	v_fma_f32 v161, |v160|, v161, s77
	v_fma_f32 v161, |v160|, v161, |v160|
	v_mul_f32_e32 v162, 0xbfb8aa3b, v161
	v_fma_f32 v163, v161, s78, -v162
	v_rndne_f32_e32 v164, v162
	v_fmac_f32_e32 v163, 0xb2a5705f, v161
	v_sub_f32_e32 v162, v162, v164
	v_add_f32_e32 v162, v162, v163
	v_cvt_i32_f32_e32 v163, v164
	v_exp_f32_e32 v162, v162
	v_cmp_nlt_f32_e32 vcc, s79, v161
	v_ldexp_f32 v162, v162, v163
	s_nop 0
	v_cndmask_b32_e32 v162, 0, v162, vcc
	v_cmp_ngt_f32_e32 vcc, s80, v161
	s_nop 1
	v_cndmask_b32_e32 v161, v3, v162, vcc
	v_sub_f32_e32 v166, 1.0, v161
	v_cmp_lt_f32_e64 vcc, |v160|, 1.0
	s_nop 1
	v_cndmask_b32_e32 v165, v166, v165, vcc
	v_bfi_b32 v165, s81, v165, v160
	v_mul_f32_e32 v161, 0.5, v168
	v_add_f32_e32 v165, 1.0, v165
	v_mul_f32_e32 v161, v161, v165
	v_mul_f32_e32 v176, v161, v4
	v_mul_f32_e32 v160, 0x3f3504f3, v169
	v_mul_f32_e32 v161, v160, v160
	v_fmamk_f32 v162, v161, 0xba1345e1, v8
	v_fmaak_f32 v162, v161, v162, 0xbcdac9b8
	v_fmaak_f32 v162, v161, v162, 0x3de703be
	v_fmaak_f32 v162, v161, v162, 0xbec09330
	v_fmaak_f32 v161, v161, v162, 0x3e0375d0
	v_fma_f32 v165, |v160|, v161, |v160|
	v_fma_f32 v161, |v160|, s72, v9
	v_fma_f32 v161, |v160|, v161, s73
	v_fma_f32 v161, |v160|, v161, s74
	v_fma_f32 v161, |v160|, v161, s75
	v_fma_f32 v161, |v160|, v161, s76
	v_fma_f32 v161, |v160|, v161, s77
	v_fma_f32 v161, |v160|, v161, |v160|
	v_mul_f32_e32 v162, 0xbfb8aa3b, v161
	v_fma_f32 v163, v161, s78, -v162
	v_rndne_f32_e32 v164, v162
	v_fmac_f32_e32 v163, 0xb2a5705f, v161
	v_sub_f32_e32 v162, v162, v164
	v_add_f32_e32 v162, v162, v163
	v_cvt_i32_f32_e32 v163, v164
	v_exp_f32_e32 v162, v162
	v_cmp_nlt_f32_e32 vcc, s79, v161
	v_ldexp_f32 v162, v162, v163
	s_nop 0
	v_cndmask_b32_e32 v162, 0, v162, vcc
	v_cmp_ngt_f32_e32 vcc, s80, v161
	s_nop 1
	v_cndmask_b32_e32 v161, v3, v162, vcc
	v_sub_f32_e32 v166, 1.0, v161
	v_cmp_lt_f32_e64 vcc, |v160|, 1.0
	s_nop 1
	v_cndmask_b32_e32 v165, v166, v165, vcc
	v_bfi_b32 v165, s81, v165, v160
	v_mul_f32_e32 v161, 0.5, v169
	v_add_f32_e32 v165, 1.0, v165
	v_mul_f32_e32 v161, v161, v165
	v_mul_f32_e32 v177, v161, v5
	v_mul_f32_e32 v160, 0x3f3504f3, v170
	v_mul_f32_e32 v161, v160, v160
	v_fmamk_f32 v162, v161, 0xba1345e1, v8
	v_fmaak_f32 v162, v161, v162, 0xbcdac9b8
	v_fmaak_f32 v162, v161, v162, 0x3de703be
	v_fmaak_f32 v162, v161, v162, 0xbec09330
	v_fmaak_f32 v161, v161, v162, 0x3e0375d0
	v_fma_f32 v165, |v160|, v161, |v160|
	v_fma_f32 v161, |v160|, s72, v9
; DEV unsigned pack2(float a, float b) { float2v v = {a, b}; return __builtin_bit_cast(unsigned, __builtin_convertvector(v, bf16x2v)); }
; DEV float bflo(unsigned u) { return __uint_as_float(u << 16); }
; DEV float bfhi(unsigned u) { return __uint_as_float(u & 0xffff0000u); }
; DEV float gelu_exact(float v) { return 0.5f * v * (1.f + erff(v * 0.7071067811865476f)); }
; DEV void ph_scan2(const Params& p, int item) {
;     ...
;   for (int t = 0; t < CHL; ++t) {
;     float4 a = *(const float4*)(p.a_arr + (row0 + t) * 1024 + ch);
;     float4 bb = *(const float4*)(p.b_arr + (row0 + t) * 1024 + ch);
;     u32x2 xg = *(const u32x2*)(p.z + (row0 + t) * ZLD + CXG + ch);
;     H[0] = a.x * H[0] + bb.x; H[1] = a.y * H[1] + bb.y; H[2] = a.z * H[2] + bb.z; H[3] = a.w * H[3] + bb.w;
;     u32x2 pk;
;     pk[0] = pack2(gelu_exact(bflo(xg[0])) * H[0], gelu_exact(bfhi(xg[0])) * H[1]);
;     pk[1] = pack2(gelu_exact(bflo(xg[1])) * H[2], gelu_exact(bfhi(xg[1])) * H[3]);
;     *(u32x2*)(p.orn + (row0 + t) * 1024 + ch) = pk;
;   }
	v_fma_f32 v161, |v160|, v161, s73
	v_fma_f32 v161, |v160|, v161, s74
	v_fma_f32 v161, |v160|, v161, s75
	v_fma_f32 v161, |v160|, v161, s76
	v_fma_f32 v161, |v160|, v161, s77
	v_fma_f32 v161, |v160|, v161, |v160|
	v_mul_f32_e32 v162, 0xbfb8aa3b, v161
	v_fma_f32 v163, v161, s78, -v162
	v_rndne_f32_e32 v164, v162
	v_fmac_f32_e32 v163, 0xb2a5705f, v161
	v_sub_f32_e32 v162, v162, v164
	v_add_f32_e32 v162, v162, v163
	v_cvt_i32_f32_e32 v163, v164
	v_exp_f32_e32 v162, v162
	v_cmp_nlt_f32_e32 vcc, s79, v161
	v_ldexp_f32 v162, v162, v163
	s_nop 0
	v_cndmask_b32_e32 v162, 0, v162, vcc
	v_cmp_ngt_f32_e32 vcc, s80, v161
	s_nop 1
	v_cndmask_b32_e32 v161, v3, v162, vcc
	v_sub_f32_e32 v166, 1.0, v161
	v_cmp_lt_f32_e64 vcc, |v160|, 1.0
	s_nop 1
	v_cndmask_b32_e32 v165, v166, v165, vcc
	v_bfi_b32 v165, s81, v165, v160
	v_mul_f32_e32 v161, 0.5, v170
	v_add_f32_e32 v165, 1.0, v165
	v_mul_f32_e32 v161, v161, v165
	v_mul_f32_e32 v178, v161, v6
	v_mul_f32_e32 v160, 0x3f3504f3, v171
	v_mul_f32_e32 v161, v160, v160
	v_fmamk_f32 v162, v161, 0xba1345e1, v8
	v_fmaak_f32 v162, v161, v162, 0xbcdac9b8
	v_fmaak_f32 v162, v161, v162, 0x3de703be
	v_fmaak_f32 v162, v161, v162, 0xbec09330
	v_fmaak_f32 v161, v161, v162, 0x3e0375d0
	v_fma_f32 v165, |v160|, v161, |v160|
	v_fma_f32 v161, |v160|, s72, v9
	v_fma_f32 v161, |v160|, v161, s73
	v_fma_f32 v161, |v160|, v161, s74
	v_fma_f32 v161, |v160|, v161, s75
	v_fma_f32 v161, |v160|, v161, s76
	v_fma_f32 v161, |v160|, v161, s77
	v_fma_f32 v161, |v160|, v161, |v160|
	v_mul_f32_e32 v162, 0xbfb8aa3b, v161
	v_fma_f32 v163, v161, s78, -v162
	v_rndne_f32_e32 v164, v162
	v_fmac_f32_e32 v163, 0xb2a5705f, v161
	v_sub_f32_e32 v162, v162, v164
	v_add_f32_e32 v162, v162, v163
	v_cvt_i32_f32_e32 v163, v164
	v_exp_f32_e32 v162, v162
	v_cmp_nlt_f32_e32 vcc, s79, v161
	v_ldexp_f32 v162, v162, v163
	s_nop 0
	v_cndmask_b32_e32 v162, 0, v162, vcc
	v_cmp_ngt_f32_e32 vcc, s80, v161
	s_nop 1
	v_cndmask_b32_e32 v161, v3, v162, vcc
	v_sub_f32_e32 v166, 1.0, v161
	v_cmp_lt_f32_e64 vcc, |v160|, 1.0
	s_nop 1
	v_cndmask_b32_e32 v165, v166, v165, vcc
	v_bfi_b32 v165, s81, v165, v160
	v_mul_f32_e32 v161, 0.5, v171
	v_add_f32_e32 v165, 1.0, v165
	v_mul_f32_e32 v161, v161, v165
	v_mul_f32_e32 v179, v161, v7
	v_cvt_pk_bf16_f32 v180, v176, v177
	v_cvt_pk_bf16_f32 v181, v178, v179
	global_store_dwordx2 v2, v[180:181], s[34:35]
	s_add_u32 s34, s34, 0x800
	s_addc_u32 s35, s35, 0
	s_waitcnt vmcnt(17)
	v_fma_f32 v4, v100, v4, v104
	v_fma_f32 v5, v101, v5, v105
	v_fma_f32 v6, v102, v6, v106
	v_fma_f32 v7, v103, v7, v107
	v_lshlrev_b32_e32 v168, 16, v108
	v_and_b32_e32 v169, 0xffff0000, v108
	v_lshlrev_b32_e32 v170, 16, v109
	v_and_b32_e32 v171, 0xffff0000, v109
	v_mul_f32_e32 v160, 0x3f3504f3, v168
	v_mul_f32_e32 v161, v160, v160
	v_fmamk_f32 v162, v161, 0xba1345e1, v8
	v_fmaak_f32 v162, v161, v162, 0xbcdac9b8
	v_fmaak_f32 v162, v161, v162, 0x3de703be
	v_fmaak_f32 v162, v161, v162, 0xbec09330
	v_fmaak_f32 v161, v161, v162, 0x3e0375d0
	v_fma_f32 v165, |v160|, v161, |v160|
	v_fma_f32 v161, |v160|, s72, v9
	v_fma_f32 v161, |v160|, v161, s73
	v_fma_f32 v161, |v160|, v161, s74
	v_fma_f32 v161, |v160|, v161, s75
	v_fma_f32 v161, |v160|, v161, s76
	v_fma_f32 v161, |v160|, v161, s77
	v_fma_f32 v161, |v160|, v161, |v160|
	v_mul_f32_e32 v162, 0xbfb8aa3b, v161
	v_fma_f32 v163, v161, s78, -v162
	v_rndne_f32_e32 v164, v162
	v_fmac_f32_e32 v163, 0xb2a5705f, v161
	v_sub_f32_e32 v162, v162, v164
	v_add_f32_e32 v162, v162, v163
	v_cvt_i32_f32_e32 v163, v164
	v_exp_f32_e32 v162, v162
	v_cmp_nlt_f32_e32 vcc, s79, v161
	v_ldexp_f32 v162, v162, v163
	s_nop 0
	v_cndmask_b32_e32 v162, 0, v162, vcc
	v_cmp_ngt_f32_e32 vcc, s80, v161
	s_nop 1
	v_cndmask_b32_e32 v161, v3, v162, vcc
	v_sub_f32_e32 v166, 1.0, v161
	v_cmp_lt_f32_e64 vcc, |v160|, 1.0
	s_nop 1
	v_cndmask_b32_e32 v165, v166, v165, vcc
	v_bfi_b32 v165, s81, v165, v160
	v_mul_f32_e32 v161, 0.5, v168
	v_add_f32_e32 v165, 1.0, v165
	v_mul_f32_e32 v161, v161, v165
	v_mul_f32_e32 v176, v161, v4
	v_mul_f32_e32 v160, 0x3f3504f3, v169
	v_mul_f32_e32 v161, v160, v160
	v_fmamk_f32 v162, v161, 0xba1345e1, v8
	v_fmaak_f32 v162, v161, v162, 0xbcdac9b8
	v_fmaak_f32 v162, v161, v162, 0x3de703be
	v_fmaak_f32 v162, v161, v162, 0xbec09330
	v_fmaak_f32 v161, v161, v162, 0x3e0375d0
	v_fma_f32 v165, |v160|, v161, |v160|
	v_fma_f32 v161, |v160|, s72, v9
	v_fma_f32 v161, |v160|, v161, s73
	v_fma_f32 v161, |v160|, v161, s74
	v_fma_f32 v161, |v160|, v161, s75
	v_fma_f32 v161, |v160|, v161, s76
	v_fma_f32 v161, |v160|, v161, s77
	v_fma_f32 v161, |v160|, v161, |v160|
	v_mul_f32_e32 v162, 0xbfb8aa3b, v161
	v_fma_f32 v163, v161, s78, -v162
	v_rndne_f32_e32 v164, v162
	v_fmac_f32_e32 v163, 0xb2a5705f, v161
	v_sub_f32_e32 v162, v162, v164
	v_add_f32_e32 v162, v162, v163
	v_cvt_i32_f32_e32 v163, v164
	v_exp_f32_e32 v162, v162
	v_cmp_nlt_f32_e32 vcc, s79, v161
	v_ldexp_f32 v162, v162, v163
	s_nop 0
	v_cndmask_b32_e32 v162, 0, v162, vcc
	v_cmp_ngt_f32_e32 vcc, s80, v161
	s_nop 1
	v_cndmask_b32_e32 v161, v3, v162, vcc
	v_sub_f32_e32 v166, 1.0, v161
	v_cmp_lt_f32_e64 vcc, |v160|, 1.0
	s_nop 1
	v_cndmask_b32_e32 v165, v166, v165, vcc
	v_bfi_b32 v165, s81, v165, v160
	v_mul_f32_e32 v161, 0.5, v169
	v_add_f32_e32 v165, 1.0, v165
	v_mul_f32_e32 v161, v161, v165
	v_mul_f32_e32 v177, v161, v5
	v_mul_f32_e32 v160, 0x3f3504f3, v170
	v_mul_f32_e32 v161, v160, v160
	v_fmamk_f32 v162, v161, 0xba1345e1, v8
	v_fmaak_f32 v162, v161, v162, 0xbcdac9b8
	v_fmaak_f32 v162, v161, v162, 0x3de703be
	v_fmaak_f32 v162, v161, v162, 0xbec09330
	v_fmaak_f32 v161, v161, v162, 0x3e0375d0
	v_fma_f32 v165, |v160|, v161, |v160|
	v_fma_f32 v161, |v160|, s72, v9
	v_fma_f32 v161, |v160|, v161, s73
; DEV unsigned pack2(float a, float b) { float2v v = {a, b}; return __builtin_bit_cast(unsigned, __builtin_convertvector(v, bf16x2v)); }
; DEV float bflo(unsigned u) { return __uint_as_float(u << 16); }
; DEV float bfhi(unsigned u) { return __uint_as_float(u & 0xffff0000u); }
; DEV float gelu_exact(float v) { return 0.5f * v * (1.f + erff(v * 0.7071067811865476f)); }
; DEV void ph_scan2(const Params& p, int item) {
;     ...
;   for (int t = 0; t < CHL; ++t) {
;     float4 a = *(const float4*)(p.a_arr + (row0 + t) * 1024 + ch);
;     float4 bb = *(const float4*)(p.b_arr + (row0 + t) * 1024 + ch);
;     u32x2 xg = *(const u32x2*)(p.z + (row0 + t) * ZLD + CXG + ch);
;     H[0] = a.x * H[0] + bb.x; H[1] = a.y * H[1] + bb.y; H[2] = a.z * H[2] + bb.z; H[3] = a.w * H[3] + bb.w;
;     u32x2 pk;
;     pk[0] = pack2(gelu_exact(bflo(xg[0])) * H[0], gelu_exact(bfhi(xg[0])) * H[1]);
;     pk[1] = pack2(gelu_exact(bflo(xg[1])) * H[2], gelu_exact(bfhi(xg[1])) * H[3]);
;     *(u32x2*)(p.orn + (row0 + t) * 1024 + ch) = pk;
;   }
	v_fma_f32 v161, |v160|, v161, s74
	v_fma_f32 v161, |v160|, v161, s75
	v_fma_f32 v161, |v160|, v161, s76
	v_fma_f32 v161, |v160|, v161, s77
	v_fma_f32 v161, |v160|, v161, |v160|
	v_mul_f32_e32 v162, 0xbfb8aa3b, v161
	v_fma_f32 v163, v161, s78, -v162
	v_rndne_f32_e32 v164, v162
	v_fmac_f32_e32 v163, 0xb2a5705f, v161
	v_sub_f32_e32 v162, v162, v164
	v_add_f32_e32 v162, v162, v163
	v_cvt_i32_f32_e32 v163, v164
	v_exp_f32_e32 v162, v162
	v_cmp_nlt_f32_e32 vcc, s79, v161
	v_ldexp_f32 v162, v162, v163
	s_nop 0
	v_cndmask_b32_e32 v162, 0, v162, vcc
	v_cmp_ngt_f32_e32 vcc, s80, v161
	s_nop 1
	v_cndmask_b32_e32 v161, v3, v162, vcc
	v_sub_f32_e32 v166, 1.0, v161
	v_cmp_lt_f32_e64 vcc, |v160|, 1.0
	s_nop 1
	v_cndmask_b32_e32 v165, v166, v165, vcc
	v_bfi_b32 v165, s81, v165, v160
	v_mul_f32_e32 v161, 0.5, v170
	v_add_f32_e32 v165, 1.0, v165
	v_mul_f32_e32 v161, v161, v165
	v_mul_f32_e32 v178, v161, v6
	v_mul_f32_e32 v160, 0x3f3504f3, v171
	v_mul_f32_e32 v161, v160, v160
	v_fmamk_f32 v162, v161, 0xba1345e1, v8
	v_fmaak_f32 v162, v161, v162, 0xbcdac9b8
	v_fmaak_f32 v162, v161, v162, 0x3de703be
	v_fmaak_f32 v162, v161, v162, 0xbec09330
	v_fmaak_f32 v161, v161, v162, 0x3e0375d0
	v_fma_f32 v165, |v160|, v161, |v160|
	v_fma_f32 v161, |v160|, s72, v9
	v_fma_f32 v161, |v160|, v161, s73
	v_fma_f32 v161, |v160|, v161, s74
	v_fma_f32 v161, |v160|, v161, s75
	v_fma_f32 v161, |v160|, v161, s76
	v_fma_f32 v161, |v160|, v161, s77
	v_fma_f32 v161, |v160|, v161, |v160|
	v_mul_f32_e32 v162, 0xbfb8aa3b, v161
	v_fma_f32 v163, v161, s78, -v162
	v_rndne_f32_e32 v164, v162
	v_fmac_f32_e32 v163, 0xb2a5705f, v161
	v_sub_f32_e32 v162, v162, v164
	v_add_f32_e32 v162, v162, v163
	v_cvt_i32_f32_e32 v163, v164
	v_exp_f32_e32 v162, v162
	v_cmp_nlt_f32_e32 vcc, s79, v161
	v_ldexp_f32 v162, v162, v163
	s_nop 0
	v_cndmask_b32_e32 v162, 0, v162, vcc
	v_cmp_ngt_f32_e32 vcc, s80, v161
	s_nop 1
	v_cndmask_b32_e32 v161, v3, v162, vcc
	v_sub_f32_e32 v166, 1.0, v161
	v_cmp_lt_f32_e64 vcc, |v160|, 1.0
	s_nop 1
	v_cndmask_b32_e32 v165, v166, v165, vcc
	v_bfi_b32 v165, s81, v165, v160
	v_mul_f32_e32 v161, 0.5, v171
	v_add_f32_e32 v165, 1.0, v165
	v_mul_f32_e32 v161, v161, v165
	v_mul_f32_e32 v179, v161, v7
	v_cvt_pk_bf16_f32 v180, v176, v177
	v_cvt_pk_bf16_f32 v181, v178, v179
	global_store_dwordx2 v2, v[180:181], s[34:35]
	s_add_u32 s34, s34, 0x800
	s_addc_u32 s35, s35, 0
	s_waitcnt vmcnt(15)
	v_fma_f32 v4, v110, v4, v114
	v_fma_f32 v5, v111, v5, v115
	v_fma_f32 v6, v112, v6, v116
	v_fma_f32 v7, v113, v7, v117
	v_lshlrev_b32_e32 v168, 16, v118
	v_and_b32_e32 v169, 0xffff0000, v118
	v_lshlrev_b32_e32 v170, 16, v119
	v_and_b32_e32 v171, 0xffff0000, v119
	v_mul_f32_e32 v160, 0x3f3504f3, v168
	v_mul_f32_e32 v161, v160, v160
	v_fmamk_f32 v162, v161, 0xba1345e1, v8
	v_fmaak_f32 v162, v161, v162, 0xbcdac9b8
	v_fmaak_f32 v162, v161, v162, 0x3de703be
	v_fmaak_f32 v162, v161, v162, 0xbec09330
	v_fmaak_f32 v161, v161, v162, 0x3e0375d0
	v_fma_f32 v165, |v160|, v161, |v160|
	v_fma_f32 v161, |v160|, s72, v9
	v_fma_f32 v161, |v160|, v161, s73
	v_fma_f32 v161, |v160|, v161, s74
	v_fma_f32 v161, |v160|, v161, s75
	v_fma_f32 v161, |v160|, v161, s76
	v_fma_f32 v161, |v160|, v161, s77
	v_fma_f32 v161, |v160|, v161, |v160|
	v_mul_f32_e32 v162, 0xbfb8aa3b, v161
	v_fma_f32 v163, v161, s78, -v162
	v_rndne_f32_e32 v164, v162
	v_fmac_f32_e32 v163, 0xb2a5705f, v161
	v_sub_f32_e32 v162, v162, v164
	v_add_f32_e32 v162, v162, v163
	v_cvt_i32_f32_e32 v163, v164
	v_exp_f32_e32 v162, v162
	v_cmp_nlt_f32_e32 vcc, s79, v161
	v_ldexp_f32 v162, v162, v163
	s_nop 0
	v_cndmask_b32_e32 v162, 0, v162, vcc
	v_cmp_ngt_f32_e32 vcc, s80, v161
	s_nop 1
	v_cndmask_b32_e32 v161, v3, v162, vcc
	v_sub_f32_e32 v166, 1.0, v161
	v_cmp_lt_f32_e64 vcc, |v160|, 1.0
	s_nop 1
	v_cndmask_b32_e32 v165, v166, v165, vcc
	v_bfi_b32 v165, s81, v165, v160
	v_mul_f32_e32 v161, 0.5, v168
	v_add_f32_e32 v165, 1.0, v165
	v_mul_f32_e32 v161, v161, v165
	v_mul_f32_e32 v176, v161, v4
	v_mul_f32_e32 v160, 0x3f3504f3, v169
	v_mul_f32_e32 v161, v160, v160
	v_fmamk_f32 v162, v161, 0xba1345e1, v8
	v_fmaak_f32 v162, v161, v162, 0xbcdac9b8
	v_fmaak_f32 v162, v161, v162, 0x3de703be
	v_fmaak_f32 v162, v161, v162, 0xbec09330
	v_fmaak_f32 v161, v161, v162, 0x3e0375d0
	v_fma_f32 v165, |v160|, v161, |v160|
	v_fma_f32 v161, |v160|, s72, v9
	v_fma_f32 v161, |v160|, v161, s73
	v_fma_f32 v161, |v160|, v161, s74
	v_fma_f32 v161, |v160|, v161, s75
	v_fma_f32 v161, |v160|, v161, s76
	v_fma_f32 v161, |v160|, v161, s77
	v_fma_f32 v161, |v160|, v161, |v160|
	v_mul_f32_e32 v162, 0xbfb8aa3b, v161
	v_fma_f32 v163, v161, s78, -v162
	v_rndne_f32_e32 v164, v162
	v_fmac_f32_e32 v163, 0xb2a5705f, v161
	v_sub_f32_e32 v162, v162, v164
	v_add_f32_e32 v162, v162, v163
	v_cvt_i32_f32_e32 v163, v164
	v_exp_f32_e32 v162, v162
	v_cmp_nlt_f32_e32 vcc, s79, v161
	v_ldexp_f32 v162, v162, v163
	s_nop 0
	v_cndmask_b32_e32 v162, 0, v162, vcc
	v_cmp_ngt_f32_e32 vcc, s80, v161
	s_nop 1
	v_cndmask_b32_e32 v161, v3, v162, vcc
	v_sub_f32_e32 v166, 1.0, v161
	v_cmp_lt_f32_e64 vcc, |v160|, 1.0
	s_nop 1
	v_cndmask_b32_e32 v165, v166, v165, vcc
	v_bfi_b32 v165, s81, v165, v160
	v_mul_f32_e32 v161, 0.5, v169
	v_add_f32_e32 v165, 1.0, v165
	v_mul_f32_e32 v161, v161, v165
	v_mul_f32_e32 v177, v161, v5
	v_mul_f32_e32 v160, 0x3f3504f3, v170
	v_mul_f32_e32 v161, v160, v160
	v_fmamk_f32 v162, v161, 0xba1345e1, v8
	v_fmaak_f32 v162, v161, v162, 0xbcdac9b8
	v_fmaak_f32 v162, v161, v162, 0x3de703be
	v_fmaak_f32 v162, v161, v162, 0xbec09330
	v_fmaak_f32 v161, v161, v162, 0x3e0375d0
	v_fma_f32 v165, |v160|, v161, |v160|
	v_fma_f32 v161, |v160|, s72, v9
	v_fma_f32 v161, |v160|, v161, s73
	v_fma_f32 v161, |v160|, v161, s74
; DEV unsigned pack2(float a, float b) { float2v v = {a, b}; return __builtin_bit_cast(unsigned, __builtin_convertvector(v, bf16x2v)); }
; DEV float bflo(unsigned u) { return __uint_as_float(u << 16); }
; DEV float bfhi(unsigned u) { return __uint_as_float(u & 0xffff0000u); }
; DEV float gelu_exact(float v) { return 0.5f * v * (1.f + erff(v * 0.7071067811865476f)); }
; DEV void ph_scan2(const Params& p, int item) {
;     ...
;   for (int t = 0; t < CHL; ++t) {
;     float4 a = *(const float4*)(p.a_arr + (row0 + t) * 1024 + ch);
;     float4 bb = *(const float4*)(p.b_arr + (row0 + t) * 1024 + ch);
;     u32x2 xg = *(const u32x2*)(p.z + (row0 + t) * ZLD + CXG + ch);
;     H[0] = a.x * H[0] + bb.x; H[1] = a.y * H[1] + bb.y; H[2] = a.z * H[2] + bb.z; H[3] = a.w * H[3] + bb.w;
;     u32x2 pk;
;     pk[0] = pack2(gelu_exact(bflo(xg[0])) * H[0], gelu_exact(bfhi(xg[0])) * H[1]);
;     pk[1] = pack2(gelu_exact(bflo(xg[1])) * H[2], gelu_exact(bfhi(xg[1])) * H[3]);
;     *(u32x2*)(p.orn + (row0 + t) * 1024 + ch) = pk;
;   }
	v_fma_f32 v161, |v160|, v161, s75
	v_fma_f32 v161, |v160|, v161, s76
	v_fma_f32 v161, |v160|, v161, s77
	v_fma_f32 v161, |v160|, v161, |v160|
	v_mul_f32_e32 v162, 0xbfb8aa3b, v161
	v_fma_f32 v163, v161, s78, -v162
	v_rndne_f32_e32 v164, v162
	v_fmac_f32_e32 v163, 0xb2a5705f, v161
	v_sub_f32_e32 v162, v162, v164
	v_add_f32_e32 v162, v162, v163
	v_cvt_i32_f32_e32 v163, v164
	v_exp_f32_e32 v162, v162
	v_cmp_nlt_f32_e32 vcc, s79, v161
	v_ldexp_f32 v162, v162, v163
	s_nop 0
	v_cndmask_b32_e32 v162, 0, v162, vcc
	v_cmp_ngt_f32_e32 vcc, s80, v161
	s_nop 1
	v_cndmask_b32_e32 v161, v3, v162, vcc
	v_sub_f32_e32 v166, 1.0, v161
	v_cmp_lt_f32_e64 vcc, |v160|, 1.0
	s_nop 1
	v_cndmask_b32_e32 v165, v166, v165, vcc
	v_bfi_b32 v165, s81, v165, v160
	v_mul_f32_e32 v161, 0.5, v170
	v_add_f32_e32 v165, 1.0, v165
	v_mul_f32_e32 v161, v161, v165
	v_mul_f32_e32 v178, v161, v6
	v_mul_f32_e32 v160, 0x3f3504f3, v171
	v_mul_f32_e32 v161, v160, v160
	v_fmamk_f32 v162, v161, 0xba1345e1, v8
	v_fmaak_f32 v162, v161, v162, 0xbcdac9b8
	v_fmaak_f32 v162, v161, v162, 0x3de703be
	v_fmaak_f32 v162, v161, v162, 0xbec09330
	v_fmaak_f32 v161, v161, v162, 0x3e0375d0
	v_fma_f32 v165, |v160|, v161, |v160|
	v_fma_f32 v161, |v160|, s72, v9
	v_fma_f32 v161, |v160|, v161, s73
	v_fma_f32 v161, |v160|, v161, s74
	v_fma_f32 v161, |v160|, v161, s75
	v_fma_f32 v161, |v160|, v161, s76
	v_fma_f32 v161, |v160|, v161, s77
	v_fma_f32 v161, |v160|, v161, |v160|
	v_mul_f32_e32 v162, 0xbfb8aa3b, v161
	v_fma_f32 v163, v161, s78, -v162
	v_rndne_f32_e32 v164, v162
	v_fmac_f32_e32 v163, 0xb2a5705f, v161
	v_sub_f32_e32 v162, v162, v164
	v_add_f32_e32 v162, v162, v163
	v_cvt_i32_f32_e32 v163, v164
	v_exp_f32_e32 v162, v162
	v_cmp_nlt_f32_e32 vcc, s79, v161
	v_ldexp_f32 v162, v162, v163
	s_nop 0
	v_cndmask_b32_e32 v162, 0, v162, vcc
	v_cmp_ngt_f32_e32 vcc, s80, v161
	s_nop 1
	v_cndmask_b32_e32 v161, v3, v162, vcc
	v_sub_f32_e32 v166, 1.0, v161
	v_cmp_lt_f32_e64 vcc, |v160|, 1.0
	s_nop 1
	v_cndmask_b32_e32 v165, v166, v165, vcc
	v_bfi_b32 v165, s81, v165, v160
	v_mul_f32_e32 v161, 0.5, v171
	v_add_f32_e32 v165, 1.0, v165
	v_mul_f32_e32 v161, v161, v165
	v_mul_f32_e32 v179, v161, v7
	v_cvt_pk_bf16_f32 v180, v176, v177
	v_cvt_pk_bf16_f32 v181, v178, v179
	global_store_dwordx2 v2, v[180:181], s[34:35]
	s_add_u32 s34, s34, 0x800
	s_addc_u32 s35, s35, 0
	s_waitcnt vmcnt(13)
	v_fma_f32 v4, v120, v4, v124
	v_fma_f32 v5, v121, v5, v125
	v_fma_f32 v6, v122, v6, v126
	v_fma_f32 v7, v123, v7, v127
	v_lshlrev_b32_e32 v168, 16, v128
	v_and_b32_e32 v169, 0xffff0000, v128
	v_lshlrev_b32_e32 v170, 16, v129
	v_and_b32_e32 v171, 0xffff0000, v129
	v_mul_f32_e32 v160, 0x3f3504f3, v168
	v_mul_f32_e32 v161, v160, v160
	v_fmamk_f32 v162, v161, 0xba1345e1, v8
	v_fmaak_f32 v162, v161, v162, 0xbcdac9b8
	v_fmaak_f32 v162, v161, v162, 0x3de703be
	v_fmaak_f32 v162, v161, v162, 0xbec09330
	v_fmaak_f32 v161, v161, v162, 0x3e0375d0
	v_fma_f32 v165, |v160|, v161, |v160|
	v_fma_f32 v161, |v160|, s72, v9
	v_fma_f32 v161, |v160|, v161, s73
	v_fma_f32 v161, |v160|, v161, s74
	v_fma_f32 v161, |v160|, v161, s75
	v_fma_f32 v161, |v160|, v161, s76
	v_fma_f32 v161, |v160|, v161, s77
	v_fma_f32 v161, |v160|, v161, |v160|
	v_mul_f32_e32 v162, 0xbfb8aa3b, v161
	v_fma_f32 v163, v161, s78, -v162
	v_rndne_f32_e32 v164, v162
	v_fmac_f32_e32 v163, 0xb2a5705f, v161
	v_sub_f32_e32 v162, v162, v164
	v_add_f32_e32 v162, v162, v163
	v_cvt_i32_f32_e32 v163, v164
	v_exp_f32_e32 v162, v162
	v_cmp_nlt_f32_e32 vcc, s79, v161
	v_ldexp_f32 v162, v162, v163
	s_nop 0
	v_cndmask_b32_e32 v162, 0, v162, vcc
	v_cmp_ngt_f32_e32 vcc, s80, v161
	s_nop 1
	v_cndmask_b32_e32 v161, v3, v162, vcc
	v_sub_f32_e32 v166, 1.0, v161
	v_cmp_lt_f32_e64 vcc, |v160|, 1.0
	s_nop 1
	v_cndmask_b32_e32 v165, v166, v165, vcc
	v_bfi_b32 v165, s81, v165, v160
	v_mul_f32_e32 v161, 0.5, v168
	v_add_f32_e32 v165, 1.0, v165
	v_mul_f32_e32 v161, v161, v165
	v_mul_f32_e32 v176, v161, v4
	v_mul_f32_e32 v160, 0x3f3504f3, v169
	v_mul_f32_e32 v161, v160, v160
	v_fmamk_f32 v162, v161, 0xba1345e1, v8
	v_fmaak_f32 v162, v161, v162, 0xbcdac9b8
	v_fmaak_f32 v162, v161, v162, 0x3de703be
	v_fmaak_f32 v162, v161, v162, 0xbec09330
	v_fmaak_f32 v161, v161, v162, 0x3e0375d0
	v_fma_f32 v165, |v160|, v161, |v160|
	v_fma_f32 v161, |v160|, s72, v9
	v_fma_f32 v161, |v160|, v161, s73
	v_fma_f32 v161, |v160|, v161, s74
	v_fma_f32 v161, |v160|, v161, s75
	v_fma_f32 v161, |v160|, v161, s76
	v_fma_f32 v161, |v160|, v161, s77
	v_fma_f32 v161, |v160|, v161, |v160|
	v_mul_f32_e32 v162, 0xbfb8aa3b, v161
	v_fma_f32 v163, v161, s78, -v162
	v_rndne_f32_e32 v164, v162
	v_fmac_f32_e32 v163, 0xb2a5705f, v161
	v_sub_f32_e32 v162, v162, v164
	v_add_f32_e32 v162, v162, v163
	v_cvt_i32_f32_e32 v163, v164
	v_exp_f32_e32 v162, v162
	v_cmp_nlt_f32_e32 vcc, s79, v161
	v_ldexp_f32 v162, v162, v163
	s_nop 0
	v_cndmask_b32_e32 v162, 0, v162, vcc
	v_cmp_ngt_f32_e32 vcc, s80, v161
	s_nop 1
	v_cndmask_b32_e32 v161, v3, v162, vcc
	v_sub_f32_e32 v166, 1.0, v161
	v_cmp_lt_f32_e64 vcc, |v160|, 1.0
	s_nop 1
	v_cndmask_b32_e32 v165, v166, v165, vcc
	v_bfi_b32 v165, s81, v165, v160
	v_mul_f32_e32 v161, 0.5, v169
	v_add_f32_e32 v165, 1.0, v165
	v_mul_f32_e32 v161, v161, v165
	v_mul_f32_e32 v177, v161, v5
	v_mul_f32_e32 v160, 0x3f3504f3, v170
	v_mul_f32_e32 v161, v160, v160
	v_fmamk_f32 v162, v161, 0xba1345e1, v8
	v_fmaak_f32 v162, v161, v162, 0xbcdac9b8
	v_fmaak_f32 v162, v161, v162, 0x3de703be
	v_fmaak_f32 v162, v161, v162, 0xbec09330
	v_fmaak_f32 v161, v161, v162, 0x3e0375d0
	v_fma_f32 v165, |v160|, v161, |v160|
	v_fma_f32 v161, |v160|, s72, v9
	v_fma_f32 v161, |v160|, v161, s73
	v_fma_f32 v161, |v160|, v161, s74
	v_fma_f32 v161, |v160|, v161, s75
; DEV unsigned pack2(float a, float b) { float2v v = {a, b}; return __builtin_bit_cast(unsigned, __builtin_convertvector(v, bf16x2v)); }
; DEV float bflo(unsigned u) { return __uint_as_float(u << 16); }
; DEV float bfhi(unsigned u) { return __uint_as_float(u & 0xffff0000u); }
; DEV float gelu_exact(float v) { return 0.5f * v * (1.f + erff(v * 0.7071067811865476f)); }
; DEV void ph_scan2(const Params& p, int item) {
;     ...
;   for (int t = 0; t < CHL; ++t) {
;     float4 a = *(const float4*)(p.a_arr + (row0 + t) * 1024 + ch);
;     float4 bb = *(const float4*)(p.b_arr + (row0 + t) * 1024 + ch);
;     u32x2 xg = *(const u32x2*)(p.z + (row0 + t) * ZLD + CXG + ch);
;     H[0] = a.x * H[0] + bb.x; H[1] = a.y * H[1] + bb.y; H[2] = a.z * H[2] + bb.z; H[3] = a.w * H[3] + bb.w;
;     u32x2 pk;
;     pk[0] = pack2(gelu_exact(bflo(xg[0])) * H[0], gelu_exact(bfhi(xg[0])) * H[1]);
;     pk[1] = pack2(gelu_exact(bflo(xg[1])) * H[2], gelu_exact(bfhi(xg[1])) * H[3]);
;     *(u32x2*)(p.orn + (row0 + t) * 1024 + ch) = pk;
;   }
	v_fma_f32 v161, |v160|, v161, s76
	v_fma_f32 v161, |v160|, v161, s77
	v_fma_f32 v161, |v160|, v161, |v160|
	v_mul_f32_e32 v162, 0xbfb8aa3b, v161
	v_fma_f32 v163, v161, s78, -v162
	v_rndne_f32_e32 v164, v162
	v_fmac_f32_e32 v163, 0xb2a5705f, v161
	v_sub_f32_e32 v162, v162, v164
	v_add_f32_e32 v162, v162, v163
	v_cvt_i32_f32_e32 v163, v164
	v_exp_f32_e32 v162, v162
	v_cmp_nlt_f32_e32 vcc, s79, v161
	v_ldexp_f32 v162, v162, v163
	s_nop 0
	v_cndmask_b32_e32 v162, 0, v162, vcc
	v_cmp_ngt_f32_e32 vcc, s80, v161
	s_nop 1
	v_cndmask_b32_e32 v161, v3, v162, vcc
	v_sub_f32_e32 v166, 1.0, v161
	v_cmp_lt_f32_e64 vcc, |v160|, 1.0
	s_nop 1
	v_cndmask_b32_e32 v165, v166, v165, vcc
	v_bfi_b32 v165, s81, v165, v160
	v_mul_f32_e32 v161, 0.5, v170
	v_add_f32_e32 v165, 1.0, v165
	v_mul_f32_e32 v161, v161, v165
	v_mul_f32_e32 v178, v161, v6
	v_mul_f32_e32 v160, 0x3f3504f3, v171
	v_mul_f32_e32 v161, v160, v160
	v_fmamk_f32 v162, v161, 0xba1345e1, v8
	v_fmaak_f32 v162, v161, v162, 0xbcdac9b8
	v_fmaak_f32 v162, v161, v162, 0x3de703be
	v_fmaak_f32 v162, v161, v162, 0xbec09330
	v_fmaak_f32 v161, v161, v162, 0x3e0375d0
	v_fma_f32 v165, |v160|, v161, |v160|
	v_fma_f32 v161, |v160|, s72, v9
	v_fma_f32 v161, |v160|, v161, s73
	v_fma_f32 v161, |v160|, v161, s74
	v_fma_f32 v161, |v160|, v161, s75
	v_fma_f32 v161, |v160|, v161, s76
	v_fma_f32 v161, |v160|, v161, s77
	v_fma_f32 v161, |v160|, v161, |v160|
	v_mul_f32_e32 v162, 0xbfb8aa3b, v161
	v_fma_f32 v163, v161, s78, -v162
	v_rndne_f32_e32 v164, v162
	v_fmac_f32_e32 v163, 0xb2a5705f, v161
	v_sub_f32_e32 v162, v162, v164
	v_add_f32_e32 v162, v162, v163
	v_cvt_i32_f32_e32 v163, v164
	v_exp_f32_e32 v162, v162
	v_cmp_nlt_f32_e32 vcc, s79, v161
	v_ldexp_f32 v162, v162, v163
	s_nop 0
	v_cndmask_b32_e32 v162, 0, v162, vcc
	v_cmp_ngt_f32_e32 vcc, s80, v161
	s_nop 1
	v_cndmask_b32_e32 v161, v3, v162, vcc
	v_sub_f32_e32 v166, 1.0, v161
	v_cmp_lt_f32_e64 vcc, |v160|, 1.0
	s_nop 1
	v_cndmask_b32_e32 v165, v166, v165, vcc
	v_bfi_b32 v165, s81, v165, v160
	v_mul_f32_e32 v161, 0.5, v171
	v_add_f32_e32 v165, 1.0, v165
	v_mul_f32_e32 v161, v161, v165
	v_mul_f32_e32 v179, v161, v7
	v_cvt_pk_bf16_f32 v180, v176, v177
	v_cvt_pk_bf16_f32 v181, v178, v179
	global_store_dwordx2 v2, v[180:181], s[34:35]
	s_add_u32 s34, s34, 0x800
	s_addc_u32 s35, s35, 0
	s_waitcnt vmcnt(11)
	v_fma_f32 v4, v130, v4, v134
	v_fma_f32 v5, v131, v5, v135
	v_fma_f32 v6, v132, v6, v136
	v_fma_f32 v7, v133, v7, v137
	v_lshlrev_b32_e32 v168, 16, v138
	v_and_b32_e32 v169, 0xffff0000, v138
	v_lshlrev_b32_e32 v170, 16, v139
	v_and_b32_e32 v171, 0xffff0000, v139
	v_mul_f32_e32 v160, 0x3f3504f3, v168
	v_mul_f32_e32 v161, v160, v160
	v_fmamk_f32 v162, v161, 0xba1345e1, v8
	v_fmaak_f32 v162, v161, v162, 0xbcdac9b8
	v_fmaak_f32 v162, v161, v162, 0x3de703be
	v_fmaak_f32 v162, v161, v162, 0xbec09330
	v_fmaak_f32 v161, v161, v162, 0x3e0375d0
	v_fma_f32 v165, |v160|, v161, |v160|
	v_fma_f32 v161, |v160|, s72, v9
	v_fma_f32 v161, |v160|, v161, s73
	v_fma_f32 v161, |v160|, v161, s74
	v_fma_f32 v161, |v160|, v161, s75
	v_fma_f32 v161, |v160|, v161, s76
	v_fma_f32 v161, |v160|, v161, s77
	v_fma_f32 v161, |v160|, v161, |v160|
	v_mul_f32_e32 v162, 0xbfb8aa3b, v161
	v_fma_f32 v163, v161, s78, -v162
	v_rndne_f32_e32 v164, v162
	v_fmac_f32_e32 v163, 0xb2a5705f, v161
	v_sub_f32_e32 v162, v162, v164
	v_add_f32_e32 v162, v162, v163
	v_cvt_i32_f32_e32 v163, v164
	v_exp_f32_e32 v162, v162
	v_cmp_nlt_f32_e32 vcc, s79, v161
	v_ldexp_f32 v162, v162, v163
	s_nop 0
	v_cndmask_b32_e32 v162, 0, v162, vcc
	v_cmp_ngt_f32_e32 vcc, s80, v161
	s_nop 1
	v_cndmask_b32_e32 v161, v3, v162, vcc
	v_sub_f32_e32 v166, 1.0, v161
	v_cmp_lt_f32_e64 vcc, |v160|, 1.0
	s_nop 1
	v_cndmask_b32_e32 v165, v166, v165, vcc
	v_bfi_b32 v165, s81, v165, v160
	v_mul_f32_e32 v161, 0.5, v168
	v_add_f32_e32 v165, 1.0, v165
	v_mul_f32_e32 v161, v161, v165
	v_mul_f32_e32 v176, v161, v4
	v_mul_f32_e32 v160, 0x3f3504f3, v169
	v_mul_f32_e32 v161, v160, v160
	v_fmamk_f32 v162, v161, 0xba1345e1, v8
	v_fmaak_f32 v162, v161, v162, 0xbcdac9b8
	v_fmaak_f32 v162, v161, v162, 0x3de703be
	v_fmaak_f32 v162, v161, v162, 0xbec09330
	v_fmaak_f32 v161, v161, v162, 0x3e0375d0
	v_fma_f32 v165, |v160|, v161, |v160|
	v_fma_f32 v161, |v160|, s72, v9
	v_fma_f32 v161, |v160|, v161, s73
	v_fma_f32 v161, |v160|, v161, s74
	v_fma_f32 v161, |v160|, v161, s75
	v_fma_f32 v161, |v160|, v161, s76
	v_fma_f32 v161, |v160|, v161, s77
	v_fma_f32 v161, |v160|, v161, |v160|
	v_mul_f32_e32 v162, 0xbfb8aa3b, v161
	v_fma_f32 v163, v161, s78, -v162
	v_rndne_f32_e32 v164, v162
	v_fmac_f32_e32 v163, 0xb2a5705f, v161
	v_sub_f32_e32 v162, v162, v164
	v_add_f32_e32 v162, v162, v163
	v_cvt_i32_f32_e32 v163, v164
	v_exp_f32_e32 v162, v162
	v_cmp_nlt_f32_e32 vcc, s79, v161
	v_ldexp_f32 v162, v162, v163
	s_nop 0
	v_cndmask_b32_e32 v162, 0, v162, vcc
	v_cmp_ngt_f32_e32 vcc, s80, v161
	s_nop 1
	v_cndmask_b32_e32 v161, v3, v162, vcc
	v_sub_f32_e32 v166, 1.0, v161
	v_cmp_lt_f32_e64 vcc, |v160|, 1.0
	s_nop 1
	v_cndmask_b32_e32 v165, v166, v165, vcc
	v_bfi_b32 v165, s81, v165, v160
	v_mul_f32_e32 v161, 0.5, v169
	v_add_f32_e32 v165, 1.0, v165
	v_mul_f32_e32 v161, v161, v165
	v_mul_f32_e32 v177, v161, v5
	v_mul_f32_e32 v160, 0x3f3504f3, v170
	v_mul_f32_e32 v161, v160, v160
	v_fmamk_f32 v162, v161, 0xba1345e1, v8
	v_fmaak_f32 v162, v161, v162, 0xbcdac9b8
	v_fmaak_f32 v162, v161, v162, 0x3de703be
	v_fmaak_f32 v162, v161, v162, 0xbec09330
	v_fmaak_f32 v161, v161, v162, 0x3e0375d0
	v_fma_f32 v165, |v160|, v161, |v160|
	v_fma_f32 v161, |v160|, s72, v9
	v_fma_f32 v161, |v160|, v161, s73
	v_fma_f32 v161, |v160|, v161, s74
	v_fma_f32 v161, |v160|, v161, s75
	v_fma_f32 v161, |v160|, v161, s76
; DEV unsigned pack2(float a, float b) { float2v v = {a, b}; return __builtin_bit_cast(unsigned, __builtin_convertvector(v, bf16x2v)); }
; DEV float bflo(unsigned u) { return __uint_as_float(u << 16); }
; DEV float bfhi(unsigned u) { return __uint_as_float(u & 0xffff0000u); }
; DEV float gelu_exact(float v) { return 0.5f * v * (1.f + erff(v * 0.7071067811865476f)); }
; DEV void ph_scan2(const Params& p, int item) {
;     ...
;   for (int t = 0; t < CHL; ++t) {
;     float4 a = *(const float4*)(p.a_arr + (row0 + t) * 1024 + ch);
;     float4 bb = *(const float4*)(p.b_arr + (row0 + t) * 1024 + ch);
;     u32x2 xg = *(const u32x2*)(p.z + (row0 + t) * ZLD + CXG + ch);
;     H[0] = a.x * H[0] + bb.x; H[1] = a.y * H[1] + bb.y; H[2] = a.z * H[2] + bb.z; H[3] = a.w * H[3] + bb.w;
;     u32x2 pk;
;     pk[0] = pack2(gelu_exact(bflo(xg[0])) * H[0], gelu_exact(bfhi(xg[0])) * H[1]);
;     pk[1] = pack2(gelu_exact(bflo(xg[1])) * H[2], gelu_exact(bfhi(xg[1])) * H[3]);
;     *(u32x2*)(p.orn + (row0 + t) * 1024 + ch) = pk;
;   }
	v_fma_f32 v161, |v160|, v161, s77
	v_fma_f32 v161, |v160|, v161, |v160|
	v_mul_f32_e32 v162, 0xbfb8aa3b, v161
	v_fma_f32 v163, v161, s78, -v162
	v_rndne_f32_e32 v164, v162
	v_fmac_f32_e32 v163, 0xb2a5705f, v161
	v_sub_f32_e32 v162, v162, v164
	v_add_f32_e32 v162, v162, v163
	v_cvt_i32_f32_e32 v163, v164
	v_exp_f32_e32 v162, v162
	v_cmp_nlt_f32_e32 vcc, s79, v161
	v_ldexp_f32 v162, v162, v163
	s_nop 0
	v_cndmask_b32_e32 v162, 0, v162, vcc
	v_cmp_ngt_f32_e32 vcc, s80, v161
	s_nop 1
	v_cndmask_b32_e32 v161, v3, v162, vcc
	v_sub_f32_e32 v166, 1.0, v161
	v_cmp_lt_f32_e64 vcc, |v160|, 1.0
	s_nop 1
	v_cndmask_b32_e32 v165, v166, v165, vcc
	v_bfi_b32 v165, s81, v165, v160
	v_mul_f32_e32 v161, 0.5, v170
	v_add_f32_e32 v165, 1.0, v165
	v_mul_f32_e32 v161, v161, v165
	v_mul_f32_e32 v178, v161, v6
	v_mul_f32_e32 v160, 0x3f3504f3, v171
	v_mul_f32_e32 v161, v160, v160
	v_fmamk_f32 v162, v161, 0xba1345e1, v8
	v_fmaak_f32 v162, v161, v162, 0xbcdac9b8
	v_fmaak_f32 v162, v161, v162, 0x3de703be
	v_fmaak_f32 v162, v161, v162, 0xbec09330
	v_fmaak_f32 v161, v161, v162, 0x3e0375d0
	v_fma_f32 v165, |v160|, v161, |v160|
	v_fma_f32 v161, |v160|, s72, v9
	v_fma_f32 v161, |v160|, v161, s73
	v_fma_f32 v161, |v160|, v161, s74
	v_fma_f32 v161, |v160|, v161, s75
	v_fma_f32 v161, |v160|, v161, s76
	v_fma_f32 v161, |v160|, v161, s77
	v_fma_f32 v161, |v160|, v161, |v160|
	v_mul_f32_e32 v162, 0xbfb8aa3b, v161
	v_fma_f32 v163, v161, s78, -v162
	v_rndne_f32_e32 v164, v162
	v_fmac_f32_e32 v163, 0xb2a5705f, v161
	v_sub_f32_e32 v162, v162, v164
	v_add_f32_e32 v162, v162, v163
	v_cvt_i32_f32_e32 v163, v164
	v_exp_f32_e32 v162, v162
	v_cmp_nlt_f32_e32 vcc, s79, v161
	v_ldexp_f32 v162, v162, v163
	s_nop 0
	v_cndmask_b32_e32 v162, 0, v162, vcc
	v_cmp_ngt_f32_e32 vcc, s80, v161
	s_nop 1
	v_cndmask_b32_e32 v161, v3, v162, vcc
	v_sub_f32_e32 v166, 1.0, v161
	v_cmp_lt_f32_e64 vcc, |v160|, 1.0
	s_nop 1
	v_cndmask_b32_e32 v165, v166, v165, vcc
	v_bfi_b32 v165, s81, v165, v160
	v_mul_f32_e32 v161, 0.5, v171
	v_add_f32_e32 v165, 1.0, v165
	v_mul_f32_e32 v161, v161, v165
	v_mul_f32_e32 v179, v161, v7
	v_cvt_pk_bf16_f32 v180, v176, v177
	v_cvt_pk_bf16_f32 v181, v178, v179
	global_store_dwordx2 v2, v[180:181], s[34:35]
	s_add_u32 s34, s34, 0x800
	s_addc_u32 s35, s35, 0
	s_waitcnt vmcnt(9)
	v_fma_f32 v4, v140, v4, v144
	v_fma_f32 v5, v141, v5, v145
	v_fma_f32 v6, v142, v6, v146
	v_fma_f32 v7, v143, v7, v147
	v_lshlrev_b32_e32 v168, 16, v148
	v_and_b32_e32 v169, 0xffff0000, v148
	v_lshlrev_b32_e32 v170, 16, v149
	v_and_b32_e32 v171, 0xffff0000, v149
	v_mul_f32_e32 v160, 0x3f3504f3, v168
	v_mul_f32_e32 v161, v160, v160
	v_fmamk_f32 v162, v161, 0xba1345e1, v8
	v_fmaak_f32 v162, v161, v162, 0xbcdac9b8
	v_fmaak_f32 v162, v161, v162, 0x3de703be
	v_fmaak_f32 v162, v161, v162, 0xbec09330
	v_fmaak_f32 v161, v161, v162, 0x3e0375d0
	v_fma_f32 v165, |v160|, v161, |v160|
	v_fma_f32 v161, |v160|, s72, v9
	v_fma_f32 v161, |v160|, v161, s73
	v_fma_f32 v161, |v160|, v161, s74
	v_fma_f32 v161, |v160|, v161, s75
	v_fma_f32 v161, |v160|, v161, s76
	v_fma_f32 v161, |v160|, v161, s77
	v_fma_f32 v161, |v160|, v161, |v160|
	v_mul_f32_e32 v162, 0xbfb8aa3b, v161
	v_fma_f32 v163, v161, s78, -v162
	v_rndne_f32_e32 v164, v162
	v_fmac_f32_e32 v163, 0xb2a5705f, v161
	v_sub_f32_e32 v162, v162, v164
	v_add_f32_e32 v162, v162, v163
	v_cvt_i32_f32_e32 v163, v164
	v_exp_f32_e32 v162, v162
	v_cmp_nlt_f32_e32 vcc, s79, v161
	v_ldexp_f32 v162, v162, v163
	s_nop 0
	v_cndmask_b32_e32 v162, 0, v162, vcc
	v_cmp_ngt_f32_e32 vcc, s80, v161
	s_nop 1
	v_cndmask_b32_e32 v161, v3, v162, vcc
	v_sub_f32_e32 v166, 1.0, v161
	v_cmp_lt_f32_e64 vcc, |v160|, 1.0
	s_nop 1
	v_cndmask_b32_e32 v165, v166, v165, vcc
	v_bfi_b32 v165, s81, v165, v160
	v_mul_f32_e32 v161, 0.5, v168
	v_add_f32_e32 v165, 1.0, v165
	v_mul_f32_e32 v161, v161, v165
	v_mul_f32_e32 v176, v161, v4
	v_mul_f32_e32 v160, 0x3f3504f3, v169
	v_mul_f32_e32 v161, v160, v160
	v_fmamk_f32 v162, v161, 0xba1345e1, v8
	v_fmaak_f32 v162, v161, v162, 0xbcdac9b8
	v_fmaak_f32 v162, v161, v162, 0x3de703be
	v_fmaak_f32 v162, v161, v162, 0xbec09330
	v_fmaak_f32 v161, v161, v162, 0x3e0375d0
	v_fma_f32 v165, |v160|, v161, |v160|
	v_fma_f32 v161, |v160|, s72, v9
	v_fma_f32 v161, |v160|, v161, s73
	v_fma_f32 v161, |v160|, v161, s74
	v_fma_f32 v161, |v160|, v161, s75
	v_fma_f32 v161, |v160|, v161, s76
	v_fma_f32 v161, |v160|, v161, s77
	v_fma_f32 v161, |v160|, v161, |v160|
	v_mul_f32_e32 v162, 0xbfb8aa3b, v161
	v_fma_f32 v163, v161, s78, -v162
	v_rndne_f32_e32 v164, v162
	v_fmac_f32_e32 v163, 0xb2a5705f, v161
	v_sub_f32_e32 v162, v162, v164
	v_add_f32_e32 v162, v162, v163
	v_cvt_i32_f32_e32 v163, v164
	v_exp_f32_e32 v162, v162
	v_cmp_nlt_f32_e32 vcc, s79, v161
	v_ldexp_f32 v162, v162, v163
	s_nop 0
	v_cndmask_b32_e32 v162, 0, v162, vcc
	v_cmp_ngt_f32_e32 vcc, s80, v161
	s_nop 1
	v_cndmask_b32_e32 v161, v3, v162, vcc
	v_sub_f32_e32 v166, 1.0, v161
	v_cmp_lt_f32_e64 vcc, |v160|, 1.0
	s_nop 1
	v_cndmask_b32_e32 v165, v166, v165, vcc
	v_bfi_b32 v165, s81, v165, v160
	v_mul_f32_e32 v161, 0.5, v169
	v_add_f32_e32 v165, 1.0, v165
	v_mul_f32_e32 v161, v161, v165
	v_mul_f32_e32 v177, v161, v5
	v_mul_f32_e32 v160, 0x3f3504f3, v170
	v_mul_f32_e32 v161, v160, v160
	v_fmamk_f32 v162, v161, 0xba1345e1, v8
	v_fmaak_f32 v162, v161, v162, 0xbcdac9b8
	v_fmaak_f32 v162, v161, v162, 0x3de703be
	v_fmaak_f32 v162, v161, v162, 0xbec09330
	v_fmaak_f32 v161, v161, v162, 0x3e0375d0
	v_fma_f32 v165, |v160|, v161, |v160|
	v_fma_f32 v161, |v160|, s72, v9
	v_fma_f32 v161, |v160|, v161, s73
	v_fma_f32 v161, |v160|, v161, s74
	v_fma_f32 v161, |v160|, v161, s75
	v_fma_f32 v161, |v160|, v161, s76
	v_fma_f32 v161, |v160|, v161, s77
; DEV unsigned pack2(float a, float b) { float2v v = {a, b}; return __builtin_bit_cast(unsigned, __builtin_convertvector(v, bf16x2v)); }
; DEV float bflo(unsigned u) { return __uint_as_float(u << 16); }
; DEV float bfhi(unsigned u) { return __uint_as_float(u & 0xffff0000u); }
; DEV float gelu_exact(float v) { return 0.5f * v * (1.f + erff(v * 0.7071067811865476f)); }
; DEV void ph_scan2(const Params& p, int item) {
;     ...
;     H[0] = a.x * H[0] + bb.x; H[1] = a.y * H[1] + bb.y; H[2] = a.z * H[2] + bb.z; H[3] = a.w * H[3] + bb.w;
;     u32x2 pk;
;     pk[0] = pack2(gelu_exact(bflo(xg[0])) * H[0], gelu_exact(bfhi(xg[0])) * H[1]);
;     pk[1] = pack2(gelu_exact(bflo(xg[1])) * H[2], gelu_exact(bfhi(xg[1])) * H[3]);
;     *(u32x2*)(p.orn + (row0 + t) * 1024 + ch) = pk;
	v_fma_f32 v161, |v160|, v161, |v160|
	v_mul_f32_e32 v162, 0xbfb8aa3b, v161
	v_fma_f32 v163, v161, s78, -v162
	v_rndne_f32_e32 v164, v162
	v_fmac_f32_e32 v163, 0xb2a5705f, v161
	v_sub_f32_e32 v162, v162, v164
	v_add_f32_e32 v162, v162, v163
	v_cvt_i32_f32_e32 v163, v164
	v_exp_f32_e32 v162, v162
	v_cmp_nlt_f32_e32 vcc, s79, v161
	v_ldexp_f32 v162, v162, v163
	s_nop 0
	v_cndmask_b32_e32 v162, 0, v162, vcc
	v_cmp_ngt_f32_e32 vcc, s80, v161
	s_nop 1
	v_cndmask_b32_e32 v161, v3, v162, vcc
	v_sub_f32_e32 v166, 1.0, v161
	v_cmp_lt_f32_e64 vcc, |v160|, 1.0
	s_nop 1
	v_cndmask_b32_e32 v165, v166, v165, vcc
	v_bfi_b32 v165, s81, v165, v160
	v_mul_f32_e32 v161, 0.5, v170
	v_add_f32_e32 v165, 1.0, v165
	v_mul_f32_e32 v161, v161, v165
	v_mul_f32_e32 v178, v161, v6
	v_mul_f32_e32 v160, 0x3f3504f3, v171
	v_mul_f32_e32 v161, v160, v160
	v_fmamk_f32 v162, v161, 0xba1345e1, v8
	v_fmaak_f32 v162, v161, v162, 0xbcdac9b8
	v_fmaak_f32 v162, v161, v162, 0x3de703be
	v_fmaak_f32 v162, v161, v162, 0xbec09330
	v_fmaak_f32 v161, v161, v162, 0x3e0375d0
	v_fma_f32 v165, |v160|, v161, |v160|
	v_fma_f32 v161, |v160|, s72, v9
	v_fma_f32 v161, |v160|, v161, s73
	v_fma_f32 v161, |v160|, v161, s74
	v_fma_f32 v161, |v160|, v161, s75
	v_fma_f32 v161, |v160|, v161, s76
	v_fma_f32 v161, |v160|, v161, s77
	v_fma_f32 v161, |v160|, v161, |v160|
	v_mul_f32_e32 v162, 0xbfb8aa3b, v161
	v_fma_f32 v163, v161, s78, -v162
	v_rndne_f32_e32 v164, v162
	v_fmac_f32_e32 v163, 0xb2a5705f, v161
	v_sub_f32_e32 v162, v162, v164
	v_add_f32_e32 v162, v162, v163
	v_cvt_i32_f32_e32 v163, v164
	v_exp_f32_e32 v162, v162
	v_cmp_nlt_f32_e32 vcc, s79, v161
	v_ldexp_f32 v162, v162, v163
	s_nop 0
	v_cndmask_b32_e32 v162, 0, v162, vcc
	v_cmp_ngt_f32_e32 vcc, s80, v161
	s_nop 1
	v_cndmask_b32_e32 v161, v3, v162, vcc
	v_sub_f32_e32 v166, 1.0, v161
	v_cmp_lt_f32_e64 vcc, |v160|, 1.0
	s_nop 1
	v_cndmask_b32_e32 v165, v166, v165, vcc
	v_bfi_b32 v165, s81, v165, v160
	v_mul_f32_e32 v161, 0.5, v171
	v_add_f32_e32 v165, 1.0, v165
	v_mul_f32_e32 v161, v161, v165
	v_mul_f32_e32 v179, v161, v7
	v_cvt_pk_bf16_f32 v180, v176, v177
	v_cvt_pk_bf16_f32 v181, v178, v179
	global_store_dwordx2 v2, v[180:181], s[34:35]
	s_add_u32 s34, s34, 0x800
	s_addc_u32 s35, s35, 0
	s_waitcnt vmcnt(7)
; DEV unsigned pack2(float a, float b) { float2v v = {a, b}; return __builtin_bit_cast(unsigned, __builtin_convertvector(v, bf16x2v)); }
; DEV float bflo(unsigned u) { return __uint_as_float(u << 16); }
; DEV float bfhi(unsigned u) { return __uint_as_float(u & 0xffff0000u); }
; DEV float gelu_exact(float v) { return 0.5f * v * (1.f + erff(v * 0.7071067811865476f)); }
; DEV void ph_scan2(const Params& p, int item) {
;     ...
;   for (int t = 0; t < CHL; ++t) {
;     float4 a = *(const float4*)(p.a_arr + (row0 + t) * 1024 + ch);
;     float4 bb = *(const float4*)(p.b_arr + (row0 + t) * 1024 + ch);
;     u32x2 xg = *(const u32x2*)(p.z + (row0 + t) * ZLD + CXG + ch);
;     H[0] = a.x * H[0] + bb.x; H[1] = a.y * H[1] + bb.y; H[2] = a.z * H[2] + bb.z; H[3] = a.w * H[3] + bb.w;
;     u32x2 pk;
;     pk[0] = pack2(gelu_exact(bflo(xg[0])) * H[0], gelu_exact(bfhi(xg[0])) * H[1]);
;     pk[1] = pack2(gelu_exact(bflo(xg[1])) * H[2], gelu_exact(bfhi(xg[1])) * H[3]);
;     *(u32x2*)(p.orn + (row0 + t) * 1024 + ch) = pk;
;   }
	v_fma_f32 v4, v150, v4, v154
	v_fma_f32 v5, v151, v5, v155
	v_fma_f32 v6, v152, v6, v156
	v_fma_f32 v7, v153, v7, v157
	v_lshlrev_b32_e32 v168, 16, v158
	v_and_b32_e32 v169, 0xffff0000, v158
	v_lshlrev_b32_e32 v170, 16, v159
	v_and_b32_e32 v171, 0xffff0000, v159
	v_mul_f32_e32 v160, 0x3f3504f3, v168
	v_mul_f32_e32 v161, v160, v160
	v_fmamk_f32 v162, v161, 0xba1345e1, v8
	v_fmaak_f32 v162, v161, v162, 0xbcdac9b8
	v_fmaak_f32 v162, v161, v162, 0x3de703be
	v_fmaak_f32 v162, v161, v162, 0xbec09330
	v_fmaak_f32 v161, v161, v162, 0x3e0375d0
	v_fma_f32 v165, |v160|, v161, |v160|
	v_fma_f32 v161, |v160|, s72, v9
	v_fma_f32 v161, |v160|, v161, s73
	v_fma_f32 v161, |v160|, v161, s74
	v_fma_f32 v161, |v160|, v161, s75
	v_fma_f32 v161, |v160|, v161, s76
	v_fma_f32 v161, |v160|, v161, s77
	v_fma_f32 v161, |v160|, v161, |v160|
	v_mul_f32_e32 v162, 0xbfb8aa3b, v161
	v_fma_f32 v163, v161, s78, -v162
	v_rndne_f32_e32 v164, v162
	v_fmac_f32_e32 v163, 0xb2a5705f, v161
	v_sub_f32_e32 v162, v162, v164
	v_add_f32_e32 v162, v162, v163
	v_cvt_i32_f32_e32 v163, v164
	v_exp_f32_e32 v162, v162
	v_cmp_nlt_f32_e32 vcc, s79, v161
	v_ldexp_f32 v162, v162, v163
	s_nop 0
	v_cndmask_b32_e32 v162, 0, v162, vcc
	v_cmp_ngt_f32_e32 vcc, s80, v161
	s_nop 1
	v_cndmask_b32_e32 v161, v3, v162, vcc
	v_sub_f32_e32 v166, 1.0, v161
	v_cmp_lt_f32_e64 vcc, |v160|, 1.0
	s_nop 1
	v_cndmask_b32_e32 v165, v166, v165, vcc
	v_bfi_b32 v165, s81, v165, v160
	v_mul_f32_e32 v161, 0.5, v168
	v_add_f32_e32 v165, 1.0, v165
	v_mul_f32_e32 v161, v161, v165
	v_mul_f32_e32 v176, v161, v4
	v_mul_f32_e32 v160, 0x3f3504f3, v169
	v_mul_f32_e32 v161, v160, v160
	v_fmamk_f32 v162, v161, 0xba1345e1, v8
	v_fmaak_f32 v162, v161, v162, 0xbcdac9b8
	v_fmaak_f32 v162, v161, v162, 0x3de703be
	v_fmaak_f32 v162, v161, v162, 0xbec09330
	v_fmaak_f32 v161, v161, v162, 0x3e0375d0
	v_fma_f32 v165, |v160|, v161, |v160|
	v_fma_f32 v161, |v160|, s72, v9
	v_fma_f32 v161, |v160|, v161, s73
	v_fma_f32 v161, |v160|, v161, s74
	v_fma_f32 v161, |v160|, v161, s75
	v_fma_f32 v161, |v160|, v161, s76
	v_fma_f32 v161, |v160|, v161, s77
	v_fma_f32 v161, |v160|, v161, |v160|
	v_mul_f32_e32 v162, 0xbfb8aa3b, v161
	v_fma_f32 v163, v161, s78, -v162
	v_rndne_f32_e32 v164, v162
	v_fmac_f32_e32 v163, 0xb2a5705f, v161
	v_sub_f32_e32 v162, v162, v164
	v_add_f32_e32 v162, v162, v163
	v_cvt_i32_f32_e32 v163, v164
	v_exp_f32_e32 v162, v162
	v_cmp_nlt_f32_e32 vcc, s79, v161
	v_ldexp_f32 v162, v162, v163
	s_nop 0
	v_cndmask_b32_e32 v162, 0, v162, vcc
	v_cmp_ngt_f32_e32 vcc, s80, v161
	s_nop 1
	v_cndmask_b32_e32 v161, v3, v162, vcc
	v_sub_f32_e32 v166, 1.0, v161
	v_cmp_lt_f32_e64 vcc, |v160|, 1.0
	s_nop 1
	v_cndmask_b32_e32 v165, v166, v165, vcc
	v_bfi_b32 v165, s81, v165, v160
	v_mul_f32_e32 v161, 0.5, v169
	v_add_f32_e32 v165, 1.0, v165
	v_mul_f32_e32 v161, v161, v165
	v_mul_f32_e32 v177, v161, v5
	v_mul_f32_e32 v160, 0x3f3504f3, v170
	v_mul_f32_e32 v161, v160, v160
	v_fmamk_f32 v162, v161, 0xba1345e1, v8
	v_fmaak_f32 v162, v161, v162, 0xbcdac9b8
	v_fmaak_f32 v162, v161, v162, 0x3de703be
	v_fmaak_f32 v162, v161, v162, 0xbec09330
	v_fmaak_f32 v161, v161, v162, 0x3e0375d0
	v_fma_f32 v165, |v160|, v161, |v160|
	v_fma_f32 v161, |v160|, s72, v9
	v_fma_f32 v161, |v160|, v161, s73
	v_fma_f32 v161, |v160|, v161, s74
	v_fma_f32 v161, |v160|, v161, s75
	v_fma_f32 v161, |v160|, v161, s76
	v_fma_f32 v161, |v160|, v161, s77
	v_fma_f32 v161, |v160|, v161, |v160|
	v_mul_f32_e32 v162, 0xbfb8aa3b, v161
	v_fma_f32 v163, v161, s78, -v162
	v_rndne_f32_e32 v164, v162
	v_fmac_f32_e32 v163, 0xb2a5705f, v161
	v_sub_f32_e32 v162, v162, v164
	v_add_f32_e32 v162, v162, v163
	v_cvt_i32_f32_e32 v163, v164
	v_exp_f32_e32 v162, v162
	v_cmp_nlt_f32_e32 vcc, s79, v161
	v_ldexp_f32 v162, v162, v163
	s_nop 0
	v_cndmask_b32_e32 v162, 0, v162, vcc
	v_cmp_ngt_f32_e32 vcc, s80, v161
	s_nop 1
	v_cndmask_b32_e32 v161, v3, v162, vcc
	v_sub_f32_e32 v166, 1.0, v161
	v_cmp_lt_f32_e64 vcc, |v160|, 1.0
	s_nop 1
	v_cndmask_b32_e32 v165, v166, v165, vcc
	v_bfi_b32 v165, s81, v165, v160
	v_mul_f32_e32 v161, 0.5, v170
	v_add_f32_e32 v165, 1.0, v165
	v_mul_f32_e32 v161, v161, v165
	v_mul_f32_e32 v178, v161, v6
	v_mul_f32_e32 v160, 0x3f3504f3, v171
	v_mul_f32_e32 v161, v160, v160
	v_fmamk_f32 v162, v161, 0xba1345e1, v8
	v_fmaak_f32 v162, v161, v162, 0xbcdac9b8
	v_fmaak_f32 v162, v161, v162, 0x3de703be
	v_fmaak_f32 v162, v161, v162, 0xbec09330
	v_fmaak_f32 v161, v161, v162, 0x3e0375d0
	v_fma_f32 v165, |v160|, v161, |v160|
	v_fma_f32 v161, |v160|, s72, v9
	v_fma_f32 v161, |v160|, v161, s73
	v_fma_f32 v161, |v160|, v161, s74
	v_fma_f32 v161, |v160|, v161, s75
	v_fma_f32 v161, |v160|, v161, s76
	v_fma_f32 v161, |v160|, v161, s77
	v_fma_f32 v161, |v160|, v161, |v160|
	v_mul_f32_e32 v162, 0xbfb8aa3b, v161
	v_fma_f32 v163, v161, s78, -v162
	v_rndne_f32_e32 v164, v162
	v_fmac_f32_e32 v163, 0xb2a5705f, v161
	v_sub_f32_e32 v162, v162, v164
	v_add_f32_e32 v162, v162, v163
	v_cvt_i32_f32_e32 v163, v164
	v_exp_f32_e32 v162, v162
	v_cmp_nlt_f32_e32 vcc, s79, v161
	v_ldexp_f32 v162, v162, v163
	s_nop 0
	v_cndmask_b32_e32 v162, 0, v162, vcc
	v_cmp_ngt_f32_e32 vcc, s80, v161
	s_nop 1
	v_cndmask_b32_e32 v161, v3, v162, vcc
	v_sub_f32_e32 v166, 1.0, v161
	v_cmp_lt_f32_e64 vcc, |v160|, 1.0
	s_nop 1
	v_cndmask_b32_e32 v165, v166, v165, vcc
	v_bfi_b32 v165, s81, v165, v160
	v_mul_f32_e32 v161, 0.5, v171
	v_add_f32_e32 v165, 1.0, v165
	v_mul_f32_e32 v161, v161, v165
	v_mul_f32_e32 v179, v161, v7
	v_cvt_pk_bf16_f32 v180, v176, v177
	v_cvt_pk_bf16_f32 v181, v178, v179
	global_store_dwordx2 v2, v[180:181], s[34:35]
	s_add_u32 s34, s34, 0x800
	s_addc_u32 s35, s35, 0
	s_add_u32 s41, s41, 1
	s_cmp_lt_u32 s41, 4
	s_cbranch_scc1 .Lsc_main
	s_cmp_gt_u32 s8, 13
	s_cbranch_scc1 .Lsc_end
	s_cmp_lg_u32 s50, s94
	s_cbranch_scc1 .Lsc_end
	s_sub_u32 s9, 31, s8
	s_lshl_b32 s9, s9, 4
	s_and_b32 s50, s94, 15
	s_add_u32 s50, s50, s9
	s_branch .Lsc_item
